# one static s_setprio 1 for waves 4-7 (younger half) around the hand-written dense and windowed attention loops, dropped at their exits
# speedup vs baseline: 1.0048x; 1.0008x over previous
.Lwa_entry:
	s_mov_b32 s40, s44
	s_load_dwordx2 s[34:35], s[64:65], 0x68
	s_mov_b64 exec, -1
	s_load_dwordx2 s[4:5], s[64:65], 0xf8
	s_mov_b32 s100, 0x3e38aa3b
	s_mov_b32 s101, 0
	v_mov_b32_e32 v86, 0x3e38aa3b
	v_and_b32_e32 v144, 63, v247
	v_lshrrev_b32_e32 v145, 6, v247
	v_and_b32_e32 v146, 15, v144
	v_lshrrev_b32_e32 v147, 4, v144
	v_readfirstlane_b32 s21, v145
	v_bfe_u32 v148, v146, 1, 3
	v_lshlrev_b32_e32 v149, 7, v146
	v_xor_b32_e32 v150, v147, v148
	v_lshl_add_u32 v136, v150, 4, v149
	v_add_u32_e32 v136, 16, v136
	v_xor_b32_e32 v150, 4, v150
	v_lshl_add_u32 v137, v150, 4, v149
	v_add_u32_e32 v137, 16, v137
	v_lshrrev_b32_e32 v151, 1, v147
	v_and_b32_e32 v152, 1, v147
	v_lshlrev_b32_e32 v152, 3, v152
	v_add_u32_e32 v152, v152, v149
	v_add_u32_e32 v152, 0x2010, v152
	v_add_u32_e32 v153, 0, v151
	v_xor_b32_e32 v153, v153, v148
	v_lshl_add_u32 v138, v153, 4, v152
	v_add_u32_e32 v153, 2, v151
	v_xor_b32_e32 v153, v153, v148
	v_lshl_add_u32 v139, v153, 4, v152
	v_add_u32_e32 v153, 4, v151
	v_xor_b32_e32 v153, v153, v148
	v_lshl_add_u32 v140, v153, 4, v152
	v_add_u32_e32 v153, 6, v151
	v_xor_b32_e32 v153, v153, v148
	v_lshl_add_u32 v141, v153, 4, v152
	s_lshl_b32 s0, s21, 3
	v_lshrrev_b32_e32 v153, 3, v144
	v_add_u32_e32 v153, s0, v153
	v_bfe_u32 v154, v153, 1, 3
	v_and_b32_e32 v155, 7, v144
	v_xor_b32_e32 v154, v154, v155
	v_lshlrev_b32_e32 v154, 4, v154
	v_mul_u32_u24_e32 v142, 0x3000, v153
	v_add_u32_e32 v142, v142, v154
	v_mul_u32_u24_e32 v143, 0x9000, v153
	v_add_u32_e32 v143, v143, v154
	s_lshl_b32 s32, s21, 10
	s_add_u32 s32, s32, 16
	s_add_u32 s41, s32, 0x2000
	s_sub_u32 s1, s40, 144
	s_waitcnt lgkmcnt(0)
	s_cmp_ge_u32 s21, 4
	s_cbranch_scc0 .Lwa_noprio
	s_setprio 1
.Lwa_noprio:
.Lwa_unit:
	v_and_b32_e32 v144, 63, v247
	s_and_b32 s80, s1, 15
	s_bfe_u32 s81, s1, 0x10004
	s_lshr_b32 s43, s1, 5
	s_lshl_b32 s33, s80, 7
	s_sub_u32 s33, s33, 128
	s_max_i32 s33, s33, 0
	s_lshl_b32 s0, s80, 7
	s_add_u32 s0, s0, 256
	s_min_u32 s0, s0, 0x800
	s_sub_u32 s0, s0, s33
	s_lshr_b32 s0, s0, 6
	s_add_u32 s45, s0, 4
	v_readlane_b32 s0, v254, 38
	s_lshl_b32 s0, s0, 4
	s_lshl_b32 s92, s81, 3
	s_add_u32 s0, s0, s92
	s_load_dwordx2 s[50:51], s[34:35], s0
	s_lshl_b32 s0, s80, 7
	s_sub_u32 s0, s0, s33
	s_lshl_b32 s92, s21, 4
	s_add_u32 s0, s0, s92
	s_add_u32 s0, s0, 128
	v_and_b32_e32 v145, 15, v144
	v_lshrrev_b32_e32 v146, 4, v144
	v_add_u32_e32 v158, s0, v145
	v_lshlrev_b32_e32 v146, 2, v146
	v_sub_u32_e32 v158, v158, v146
	v_mov_b32_e32 v159, 0xf149f2ca
	s_lshl_b32 s0, s81, 7
	s_add_u32 s0, s0, 0x200
	s_add_u32 s6, s4, 0x9f00000
	s_addc_u32 s7, s5, 0
	s_add_u32 s6, s6, s0
	s_addc_u32 s7, s7, 0
	s_mul_i32 s0, s43, 0x1800000
	s_add_u32 s96, s6, s0
	s_addc_u32 s97, s7, 0
	s_mul_i32 s0, s33, 0x3000
	s_add_u32 s96, s96, s0
	s_addc_u32 s97, s97, 0
	s_mul_i32 s0, s43, 0x300000
	s_add_u32 s6, s6, s0
	s_addc_u32 s7, s7, 0
	s_add_u32 s6, s6, 0xc000000
	s_addc_u32 s7, s7, 0
	s_lshl_b32 s0, s81, 6
	s_mul_i32 s0, s0, 0x9000
	s_add_u32 s8, s4, 0x17700000
	s_addc_u32 s9, s5, 0
	s_add_u32 s8, s8, s0
	s_addc_u32 s9, s9, 0
	s_lshl_b32 s0, s43, 12
	s_add_u32 s98, s8, s0
	s_addc_u32 s99, s9, 0
	s_lshl_b32 s0, s33, 1
	s_add_u32 s98, s98, s0
	s_addc_u32 s99, s99, 0
	s_lshl_b32 s0, s43, 9
	s_add_u32 s0, s0, 0x8000
	s_add_u32 s8, s8, s0
	s_addc_u32 s9, s9, 0
	s_lshl_b32 s0, s43, 11
	s_lshl_b32 s92, s80, 7
	s_add_u32 s0, s0, s92
	s_lshl_b32 s92, s21, 4
	s_add_u32 s0, s0, s92
	v_and_b32_e32 v146, 15, v144
	v_add_u32_e32 v146, s0, v146
	v_lshrrev_b32_e32 v147, 4, v144
	s_lshl_b32 s92, s81, 8
	v_lshl_add_u32 v148, v147, 4, s92
	v_mov_b32_e32 v149, 0
	s_movk_i32 s93, 0x3000
	v_mad_u64_u32 v[82:83], s[90:91], v146, s93, v[148:149]
	s_add_u32 s90, s4, 0x9f00000
	s_addc_u32 s91, s5, 0
	v_lshl_add_u64 v[82:83], v[82:83], 0, s[90:91]
	global_load_dwordx4 v[2:5], v[82:83], off
	global_load_dwordx4 v[6:9], v[82:83], off offset:64
	global_load_dwordx4 v[10:13], v[82:83], off offset:128
	global_load_dwordx4 v[14:17], v[82:83], off offset:192
	s_lshl_b32 s92, s81, 8
	v_lshl_add_u32 v148, v147, 3, s92
	v_lshlrev_b32_e32 v150, 11, v146
	v_add_u32_e32 v148, v148, v150
	s_add_u32 s90, s4, 0x1e300000
	s_addc_u32 s91, s5, 0
	v_lshl_add_u64 v[84:85], s[90:91], 0, v[148:149]
	v_mov_b32_e32 v100, 0
	v_mov_b32_e32 v101, 0
	v_mov_b32_e32 v102, 0
	v_mov_b32_e32 v103, 0
	v_mov_b32_e32 v104, 0
	v_mov_b32_e32 v105, 0
	v_mov_b32_e32 v106, 0
	v_mov_b32_e32 v107, 0
	v_mov_b32_e32 v108, 0
	v_mov_b32_e32 v109, 0
	v_mov_b32_e32 v110, 0
	v_mov_b32_e32 v111, 0
	v_mov_b32_e32 v112, 0
	v_mov_b32_e32 v113, 0
	v_mov_b32_e32 v114, 0
	v_mov_b32_e32 v115, 0
	v_mov_b32_e32 v116, 0
	v_mov_b32_e32 v117, 0
	v_mov_b32_e32 v118, 0
	v_mov_b32_e32 v119, 0
	v_mov_b32_e32 v120, 0
	v_mov_b32_e32 v121, 0
	v_mov_b32_e32 v122, 0
	v_mov_b32_e32 v123, 0
	v_mov_b32_e32 v124, 0
	v_mov_b32_e32 v125, 0
	v_mov_b32_e32 v126, 0
	v_mov_b32_e32 v127, 0
	v_mov_b32_e32 v128, 0
	v_mov_b32_e32 v129, 0
	v_mov_b32_e32 v130, 0
	v_mov_b32_e32 v131, 0
	v_mov_b32_e32 v132, 0xf149f2ca
	v_mov_b32_e32 v133, 0xf149f2ca
	v_mov_b32_e32 v134, 0
	v_mov_b32_e32 v135, 0
	s_mov_b32 s89, 0
	s_mov_b32 s42, s45
	s_mov_b32 s90, 0
	s_barrier
	s_cmp_eq_u32 s89, 4
	s_cbranch_scc0 .Lwa_nosw1
	s_mov_b64 s[6:7], s[96:97]
	s_mov_b64 s[8:9], s[98:99]

.Lwa_done:
	s_setprio 0
	s_barrier
	s_sub_u32 s4, s40, 144
	s_add_u32 s4, s4, 0x200
	s_movk_i32 s0, 0x2a0
	s_movk_i32 s1, 0x70
	s_branch .LBB0_627

.Lga_entry:
	s_mov_b64 exec, -1
	s_load_dwordx2 s[4:5], s[64:65], 0xf8
	s_mov_b32 s100, 0x3e38aa3b
	s_mov_b32 s101, 0
	v_mov_b32_e32 v86, 0x3e38aa3b
	v_and_b32_e32 v144, 63, v247
	v_lshrrev_b32_e32 v145, 6, v247
	v_and_b32_e32 v146, 15, v144
	v_lshrrev_b32_e32 v147, 4, v144
	v_readfirstlane_b32 s21, v145
	v_bfe_u32 v148, v146, 1, 3
	v_lshlrev_b32_e32 v149, 7, v146
	v_xor_b32_e32 v150, v147, v148
	v_lshl_add_u32 v136, v150, 4, v149
	v_add_u32_e32 v136, 16, v136
	v_xor_b32_e32 v150, 4, v150
	v_lshl_add_u32 v137, v150, 4, v149
	v_add_u32_e32 v137, 16, v137
	v_lshrrev_b32_e32 v151, 1, v147
	v_and_b32_e32 v152, 1, v147
	v_lshlrev_b32_e32 v152, 3, v152
	v_add_u32_e32 v152, v152, v149
	v_add_u32_e32 v152, 0x2010, v152
	v_add_u32_e32 v153, 0, v151
	v_xor_b32_e32 v153, v153, v148
	v_lshl_add_u32 v138, v153, 4, v152
	v_add_u32_e32 v153, 2, v151
	v_xor_b32_e32 v153, v153, v148
	v_lshl_add_u32 v139, v153, 4, v152
	v_add_u32_e32 v153, 4, v151
	v_xor_b32_e32 v153, v153, v148
	v_lshl_add_u32 v140, v153, 4, v152
	v_add_u32_e32 v153, 6, v151
	v_xor_b32_e32 v153, v153, v148
	v_lshl_add_u32 v141, v153, 4, v152
	s_lshl_b32 s0, s21, 3
	v_lshrrev_b32_e32 v153, 3, v144
	v_add_u32_e32 v153, s0, v153
	v_bfe_u32 v154, v153, 1, 3
	v_and_b32_e32 v155, 7, v144
	v_xor_b32_e32 v154, v154, v155
	v_lshlrev_b32_e32 v154, 4, v154
	v_mul_u32_u24_e32 v142, 0x3000, v153
	v_add_u32_e32 v142, v142, v154
	v_mul_u32_u24_e32 v143, 0x9000, v153
	v_add_u32_e32 v143, v143, v154
	s_lshl_b32 s32, s21, 10
	s_add_u32 s32, s32, 16
	s_add_u32 s41, s32, 0x2000
	s_sub_u32 s1, s40, 144
	s_waitcnt lgkmcnt(0)
	s_cmp_ge_u32 s21, 4
	s_cbranch_scc0 .Lga_noprio
	s_setprio 1
.Lga_noprio:
.Lga_unit:
	v_and_b32_e32 v144, 63, v247
	s_and_b32 s80, s1, 15
	s_bfe_u32 s81, s1, 0x10004
	s_lshr_b32 s43, s1, 5
	s_lshl_b32 s0, s81, 7
	s_add_u32 s0, s0, 0x900
	s_add_u32 s6, s4, 0x9f00000
	s_addc_u32 s7, s5, 0
	s_add_u32 s6, s6, s0
	s_addc_u32 s7, s7, 0
	s_mul_i32 s0, s43, 0x1800000
	s_add_u32 s96, s6, s0
	s_addc_u32 s97, s7, 0
	s_mul_i32 s0, s43, 0x300000
	s_add_u32 s6, s6, s0
	s_addc_u32 s7, s7, 0
	s_add_u32 s6, s6, 0xc000000
	s_addc_u32 s7, s7, 0
	s_lshl_b32 s0, s81, 6
	s_add_u32 s0, s0, 0x180
	s_mul_i32 s0, s0, 0x9000
	s_add_u32 s8, s4, 0x17700000
	s_addc_u32 s9, s5, 0
	s_add_u32 s8, s8, s0
	s_addc_u32 s9, s9, 0
	s_lshl_b32 s0, s43, 12
	s_add_u32 s98, s8, s0
	s_addc_u32 s99, s9, 0
	s_lshl_b32 s0, s43, 9
	s_add_u32 s0, s0, 0x8000
	s_add_u32 s8, s8, s0
	s_addc_u32 s9, s9, 0
	s_lshl_b32 s0, s43, 11
	s_lshl_b32 s92, s80, 7
	s_add_u32 s0, s0, s92
	s_lshl_b32 s92, s21, 4
	s_add_u32 s0, s0, s92
	v_and_b32_e32 v146, 15, v144
	v_add_u32_e32 v146, s0, v146
	v_lshrrev_b32_e32 v147, 4, v144
	s_lshl_b32 s92, s81, 8
	s_add_u32 s92, s92, 0x700
	v_lshl_add_u32 v148, v147, 4, s92
	v_mov_b32_e32 v149, 0
	s_movk_i32 s93, 0x3000
	v_mad_u64_u32 v[82:83], s[90:91], v146, s93, v[148:149]
	s_add_u32 s90, s4, 0x9f00000
	s_addc_u32 s91, s5, 0
	v_lshl_add_u64 v[82:83], v[82:83], 0, s[90:91]
	global_load_dwordx4 v[2:5], v[82:83], off
	global_load_dwordx4 v[6:9], v[82:83], off offset:64
	global_load_dwordx4 v[10:13], v[82:83], off offset:128
	global_load_dwordx4 v[14:17], v[82:83], off offset:192
	s_lshl_b32 s92, s81, 8
	s_add_u32 s92, s92, 0x400
	v_lshl_add_u32 v148, v147, 3, s92
	v_lshlrev_b32_e32 v150, 11, v146
	v_add_u32_e32 v148, v148, v150
	s_add_u32 s90, s4, 0x1e300000
	s_addc_u32 s91, s5, 0
	v_lshl_add_u64 v[84:85], s[90:91], 0, v[148:149]
	v_mov_b32_e32 v100, 0
	v_mov_b32_e32 v101, 0
	v_mov_b32_e32 v102, 0
	v_mov_b32_e32 v103, 0
	v_mov_b32_e32 v104, 0
	v_mov_b32_e32 v105, 0
	v_mov_b32_e32 v106, 0
	v_mov_b32_e32 v107, 0
	v_mov_b32_e32 v108, 0
	v_mov_b32_e32 v109, 0
	v_mov_b32_e32 v110, 0
	v_mov_b32_e32 v111, 0
	v_mov_b32_e32 v112, 0
	v_mov_b32_e32 v113, 0
	v_mov_b32_e32 v114, 0
	v_mov_b32_e32 v115, 0
	v_mov_b32_e32 v116, 0
	v_mov_b32_e32 v117, 0
	v_mov_b32_e32 v118, 0
	v_mov_b32_e32 v119, 0
	v_mov_b32_e32 v120, 0
	v_mov_b32_e32 v121, 0
	v_mov_b32_e32 v122, 0
	v_mov_b32_e32 v123, 0
	v_mov_b32_e32 v124, 0
	v_mov_b32_e32 v125, 0
	v_mov_b32_e32 v126, 0
	v_mov_b32_e32 v127, 0
	v_mov_b32_e32 v128, 0
	v_mov_b32_e32 v129, 0
	v_mov_b32_e32 v130, 0
	v_mov_b32_e32 v131, 0
	v_mov_b32_e32 v132, 0xf149f2ca
	v_mov_b32_e32 v133, 0xf149f2ca
	v_mov_b32_e32 v134, 0
	v_mov_b32_e32 v135, 0
	s_mov_b32 s89, 0
	s_mov_b32 s42, 36
	s_barrier
	s_cmp_eq_u32 s89, 4
	s_cbranch_scc0 .Lga_nosw1
	s_mov_b64 s[6:7], s[96:97]
	s_mov_b64 s[8:9], s[98:99]

.Lga_done:
	s_setprio 0
	s_branch .LBB0_979
